# final rmsnorm: gains loaded once, one row prefetched ahead
# speedup vs baseline: 1.0073x; 1.0073x over previous
; __device__ __forceinline__ float bflo(unsigned w) { return __uint_as_float(w << 16); }
; __device__ __forceinline__ float bfhi(unsigned w) { return __uint_as_float(w & 0xffff0000u); }
; __device__ __forceinline__ void phase_final_norm(const bf16_t* Hb, const unsigned long long* ssq, const float* g, float* out, int gw, int ngw, int lane, float scale) {
;     for (int m = gw; m < MTOK; m += ngw) { const float rstd = scale / sqrtf((float)ssq[m] * (1.0f / 16777216.0f) * (1.0f / DM) + EPS);
;         const u32x4* xr = (const u32x4*)(Hb + (size_t)m * DM) + lane; f32x4* o = (f32x4*)(out + (size_t)m * DM); const f32x4* gr = (const f32x4*)g;
; #pragma unroll
;         for (int j = 0; j < 8; ++j) { const u32x4 r = xr[64 * j]; const int c4 = 2 * (64 * j + lane);
;             const f32x4 g0 = gr[c4], g1 = gr[c4 + 1];
;             o[c4] = (f32x4){bflo(r.x) * rstd * g0.x, bfhi(r.x) * rstd * g0.y, bflo(r.y) * rstd * g0.z, bfhi(r.y) * rstd * g0.w};
;             o[c4 + 1] = (f32x4){bflo(r.z) * rstd * g1.x, bfhi(r.z) * rstd * g1.y, bflo(r.w) * rstd * g1.z, bfhi(r.w) * rstd * g1.w}; } }
.Lfn_entry:
	v_lshlrev_b32_e32 v2, 4, v164
	v_lshlrev_b32_e32 v3, 5, v164
	v_mov_b32_e32 v232, 0
	s_add_u32 s20, s54, 0x1000
	s_addc_u32 s21, s55, 0
	s_add_u32 s22, s54, 0x2000
	s_addc_u32 s23, s55, 0
	s_add_u32 s24, s54, 0x3000
	s_addc_u32 s25, s55, 0
	global_load_dwordx4 v[8:11], v3, s[54:55] offset:0
	global_load_dwordx4 v[12:15], v3, s[54:55] offset:16
	global_load_dwordx4 v[16:19], v3, s[54:55] offset:2048
	global_load_dwordx4 v[20:23], v3, s[54:55] offset:2064
	global_load_dwordx4 v[24:27], v3, s[20:21] offset:0
	global_load_dwordx4 v[28:31], v3, s[20:21] offset:16
	global_load_dwordx4 v[32:35], v3, s[20:21] offset:2048
	global_load_dwordx4 v[36:39], v3, s[20:21] offset:2064
	global_load_dwordx4 v[40:43], v3, s[22:23] offset:0
	global_load_dwordx4 v[44:47], v3, s[22:23] offset:16
	global_load_dwordx4 v[48:51], v3, s[22:23] offset:2048
	global_load_dwordx4 v[52:55], v3, s[22:23] offset:2064
	global_load_dwordx4 v[56:59], v3, s[24:25] offset:0
	global_load_dwordx4 v[60:63], v3, s[24:25] offset:16
	global_load_dwordx4 v[64:67], v3, s[24:25] offset:2048
	global_load_dwordx4 v[68:71], v3, s[24:25] offset:2064
	s_add_u32 s4, s58, 0xb0000
	s_addc_u32 s5, s59, 0
	s_add_u32 s6, s58, 0x2f800000
	s_addc_u32 s7, s59, 0
	s_mul_i32 s26, s74, 0
	s_add_i32 s26, s26, s52
	s_lshl_b32 s27, s26, 3
	s_add_u32 s8, s4, s27
	s_addc_u32 s9, s5, 0
	global_load_dwordx2 v[200:201], v232, s[8:9]
	s_lshl_b32 s27, s26, 13
	s_add_u32 s8, s6, s27
	s_addc_u32 s9, s7, 0
	s_add_u32 s10, s8, 0x1000
	s_addc_u32 s11, s9, 0
	global_load_dwordx4 v[72:75], v2, s[8:9] offset:0
	global_load_dwordx4 v[76:79], v2, s[8:9] offset:1024
	global_load_dwordx4 v[80:83], v2, s[8:9] offset:2048
	global_load_dwordx4 v[84:87], v2, s[8:9] offset:3072
	global_load_dwordx4 v[88:91], v2, s[10:11] offset:0
	global_load_dwordx4 v[92:95], v2, s[10:11] offset:1024
	global_load_dwordx4 v[96:99], v2, s[10:11] offset:2048
	global_load_dwordx4 v[100:103], v2, s[10:11] offset:3072
	s_mul_i32 s26, s74, 1
	s_add_i32 s26, s26, s52
	s_lshl_b32 s27, s26, 3
	s_add_u32 s8, s4, s27
	s_addc_u32 s9, s5, 0
	global_load_dwordx2 v[202:203], v232, s[8:9]
	s_lshl_b32 s27, s26, 13
	s_add_u32 s8, s6, s27
	s_addc_u32 s9, s7, 0
	s_add_u32 s10, s8, 0x1000
	s_addc_u32 s11, s9, 0
	global_load_dwordx4 v[104:107], v2, s[8:9] offset:0
	global_load_dwordx4 v[108:111], v2, s[8:9] offset:1024
	global_load_dwordx4 v[112:115], v2, s[8:9] offset:2048
	global_load_dwordx4 v[116:119], v2, s[8:9] offset:3072
	global_load_dwordx4 v[120:123], v2, s[10:11] offset:0
	global_load_dwordx4 v[124:127], v2, s[10:11] offset:1024
	global_load_dwordx4 v[128:131], v2, s[10:11] offset:2048
	global_load_dwordx4 v[132:135], v2, s[10:11] offset:3072
	v_mov_b32_e32 v233, 0x358637bd
	v_mov_b32_e32 v234, 0x260
	s_mov_b32 s28, 0xf800000
	s_mul_i32 s26, s74, 0
	s_add_i32 s26, s26, s52
	s_lshl_b32 s27, s26, 14
	s_add_u32 s12, s56, s27
	s_addc_u32 s13, s57, 0
	s_add_u32 s14, s12, 0x1000
	s_addc_u32 s15, s13, 0
	s_add_u32 s16, s14, 0x1000
	s_addc_u32 s17, s15, 0
	s_add_u32 s18, s16, 0x1000
	s_addc_u32 s19, s17, 0
	s_waitcnt vmcnt(9)
	v_ffbh_u32_e32 v208, v201
	v_min_u32_e32 v208, 32, v208
	v_lshlrev_b64 v[200:201], v208, v[200:201]
	v_min_u32_e32 v200, 1, v200
	v_or_b32_e32 v200, v201, v200
	v_cvt_f32_u32_e32 v200, v200
	v_sub_u32_e32 v208, 32, v208
	v_ldexp_f32 v208, v200, v208
	v_mul_f32_e32 v208, 0x33800000, v208
	v_fmamk_f32 v208, v208, 0x39800000, v233
	v_mul_f32_e32 v209, 0x4f800000, v208
	v_cmp_gt_f32_e32 vcc, s28, v208
	s_nop 1
	v_cndmask_b32_e32 v208, v208, v209, vcc
	v_sqrt_f32_e32 v209, v208
	s_nop 1
	v_add_u32_e32 v210, -1, v209
	v_add_u32_e32 v211, 1, v209
	v_fma_f32 v212, -v210, v209, v208
	v_fma_f32 v213, -v211, v209, v208
	v_cmp_ge_f32_e64 s[0:1], 0, v212
	s_nop 1
	v_cndmask_b32_e64 v209, v209, v210, s[0:1]
	v_cmp_lt_f32_e64 s[0:1], 0, v213
	s_nop 1
	v_cndmask_b32_e64 v209, v209, v211, s[0:1]
	v_mul_f32_e32 v210, 0x37800000, v209
	v_cndmask_b32_e32 v209, v209, v210, vcc
	v_cmp_class_f32_e32 vcc, v208, v234
	s_nop 1
	v_cndmask_b32_e32 v208, v209, v208, vcc
	v_div_scale_f32 v209, s[0:1], v208, v208, 1.0
	v_rcp_f32_e32 v211, v209
	v_div_scale_f32 v210, vcc, 1.0, v208, 1.0
	s_nop 0
	v_fma_f32 v212, -v209, v211, 1.0
	v_fmac_f32_e32 v211, v212, v211
	v_mul_f32_e32 v212, v210, v211
	v_fma_f32 v213, -v209, v212, v210
	v_fmac_f32_e32 v212, v213, v211
	v_fma_f32 v209, -v209, v212, v210
	s_nop 1
	v_div_fmas_f32 v209, v209, v211, v212
	v_div_fixup_f32 v214, v209, v208, 1.0
	v_mov_b32_e32 v215, v214
	v_lshlrev_b32_e32 v216, 16, v72
	v_and_b32_e32 v217, 0xffff0000, v72
	v_lshlrev_b32_e32 v218, 16, v73
	v_and_b32_e32 v219, 0xffff0000, v73
	v_lshlrev_b32_e32 v220, 16, v74
	v_and_b32_e32 v221, 0xffff0000, v74
	v_lshlrev_b32_e32 v222, 16, v75
	v_and_b32_e32 v223, 0xffff0000, v75
	v_pk_mul_f32 v[216:217], v[214:215], v[216:217]
	v_pk_mul_f32 v[218:219], v[214:215], v[218:219]
	v_pk_mul_f32 v[220:221], v[214:215], v[220:221]
	v_pk_mul_f32 v[222:223], v[214:215], v[222:223]
	v_pk_mul_f32 v[216:217], v[8:9], v[216:217]
	v_pk_mul_f32 v[218:219], v[10:11], v[218:219]
	v_pk_mul_f32 v[220:221], v[12:13], v[220:221]
	v_pk_mul_f32 v[222:223], v[14:15], v[222:223]
	global_store_dwordx4 v3, v[216:219], s[12:13] offset:0
	global_store_dwordx4 v3, v[220:223], s[12:13] offset:16
	v_lshlrev_b32_e32 v224, 16, v76
	v_and_b32_e32 v225, 0xffff0000, v76
	v_lshlrev_b32_e32 v226, 16, v77
	v_and_b32_e32 v227, 0xffff0000, v77
	v_lshlrev_b32_e32 v228, 16, v78
	v_and_b32_e32 v229, 0xffff0000, v78
	v_lshlrev_b32_e32 v230, 16, v79
	v_and_b32_e32 v231, 0xffff0000, v79
	v_pk_mul_f32 v[224:225], v[214:215], v[224:225]
	v_pk_mul_f32 v[226:227], v[214:215], v[226:227]
; __device__ __forceinline__ float bflo(unsigned w) { return __uint_as_float(w << 16); }
; __device__ __forceinline__ float bfhi(unsigned w) { return __uint_as_float(w & 0xffff0000u); }
; __device__ __forceinline__ void phase_final_norm(const bf16_t* Hb, const unsigned long long* ssq, const float* g, float* out, int gw, int ngw, int lane, float scale) {
;     for (int m = gw; m < MTOK; m += ngw) { const float rstd = scale / sqrtf((float)ssq[m] * (1.0f / 16777216.0f) * (1.0f / DM) + EPS);
;         const u32x4* xr = (const u32x4*)(Hb + (size_t)m * DM) + lane; f32x4* o = (f32x4*)(out + (size_t)m * DM); const f32x4* gr = (const f32x4*)g;
; #pragma unroll
;         for (int j = 0; j < 8; ++j) { const u32x4 r = xr[64 * j]; const int c4 = 2 * (64 * j + lane);
;             const f32x4 g0 = gr[c4], g1 = gr[c4 + 1];
;             o[c4] = (f32x4){bflo(r.x) * rstd * g0.x, bfhi(r.x) * rstd * g0.y, bflo(r.y) * rstd * g0.z, bfhi(r.y) * rstd * g0.w};
;             o[c4 + 1] = (f32x4){bflo(r.z) * rstd * g1.x, bfhi(r.z) * rstd * g1.y, bflo(r.w) * rstd * g1.z, bfhi(r.w) * rstd * g1.w}; } }
	v_pk_mul_f32 v[228:229], v[214:215], v[228:229]
	v_pk_mul_f32 v[230:231], v[214:215], v[230:231]
	v_pk_mul_f32 v[224:225], v[16:17], v[224:225]
	v_pk_mul_f32 v[226:227], v[18:19], v[226:227]
	v_pk_mul_f32 v[228:229], v[20:21], v[228:229]
	v_pk_mul_f32 v[230:231], v[22:23], v[230:231]
	global_store_dwordx4 v3, v[224:227], s[12:13] offset:2048
	global_store_dwordx4 v3, v[228:231], s[12:13] offset:2064
	v_lshlrev_b32_e32 v216, 16, v80
	v_and_b32_e32 v217, 0xffff0000, v80
	v_lshlrev_b32_e32 v218, 16, v81
	v_and_b32_e32 v219, 0xffff0000, v81
	v_lshlrev_b32_e32 v220, 16, v82
	v_and_b32_e32 v221, 0xffff0000, v82
	v_lshlrev_b32_e32 v222, 16, v83
	v_and_b32_e32 v223, 0xffff0000, v83
	v_pk_mul_f32 v[216:217], v[214:215], v[216:217]
	v_pk_mul_f32 v[218:219], v[214:215], v[218:219]
	v_pk_mul_f32 v[220:221], v[214:215], v[220:221]
	v_pk_mul_f32 v[222:223], v[214:215], v[222:223]
	v_pk_mul_f32 v[216:217], v[24:25], v[216:217]
	v_pk_mul_f32 v[218:219], v[26:27], v[218:219]
	v_pk_mul_f32 v[220:221], v[28:29], v[220:221]
	v_pk_mul_f32 v[222:223], v[30:31], v[222:223]
	global_store_dwordx4 v3, v[216:219], s[14:15] offset:0
	global_store_dwordx4 v3, v[220:223], s[14:15] offset:16
	v_lshlrev_b32_e32 v224, 16, v84
	v_and_b32_e32 v225, 0xffff0000, v84
	v_lshlrev_b32_e32 v226, 16, v85
	v_and_b32_e32 v227, 0xffff0000, v85
	v_lshlrev_b32_e32 v228, 16, v86
	v_and_b32_e32 v229, 0xffff0000, v86
	v_lshlrev_b32_e32 v230, 16, v87
	v_and_b32_e32 v231, 0xffff0000, v87
	v_pk_mul_f32 v[224:225], v[214:215], v[224:225]
	v_pk_mul_f32 v[226:227], v[214:215], v[226:227]
	v_pk_mul_f32 v[228:229], v[214:215], v[228:229]
	v_pk_mul_f32 v[230:231], v[214:215], v[230:231]
	v_pk_mul_f32 v[224:225], v[32:33], v[224:225]
	v_pk_mul_f32 v[226:227], v[34:35], v[226:227]
	v_pk_mul_f32 v[228:229], v[36:37], v[228:229]
	v_pk_mul_f32 v[230:231], v[38:39], v[230:231]
	global_store_dwordx4 v3, v[224:227], s[14:15] offset:2048
	global_store_dwordx4 v3, v[228:231], s[14:15] offset:2064
	v_lshlrev_b32_e32 v216, 16, v88
	v_and_b32_e32 v217, 0xffff0000, v88
	v_lshlrev_b32_e32 v218, 16, v89
	v_and_b32_e32 v219, 0xffff0000, v89
	v_lshlrev_b32_e32 v220, 16, v90
	v_and_b32_e32 v221, 0xffff0000, v90
	v_lshlrev_b32_e32 v222, 16, v91
	v_and_b32_e32 v223, 0xffff0000, v91
	v_pk_mul_f32 v[216:217], v[214:215], v[216:217]
	v_pk_mul_f32 v[218:219], v[214:215], v[218:219]
	v_pk_mul_f32 v[220:221], v[214:215], v[220:221]
	v_pk_mul_f32 v[222:223], v[214:215], v[222:223]
	v_pk_mul_f32 v[216:217], v[40:41], v[216:217]
	v_pk_mul_f32 v[218:219], v[42:43], v[218:219]
	v_pk_mul_f32 v[220:221], v[44:45], v[220:221]
	v_pk_mul_f32 v[222:223], v[46:47], v[222:223]
	global_store_dwordx4 v3, v[216:219], s[16:17] offset:0
	global_store_dwordx4 v3, v[220:223], s[16:17] offset:16
	v_lshlrev_b32_e32 v224, 16, v92
	v_and_b32_e32 v225, 0xffff0000, v92
	v_lshlrev_b32_e32 v226, 16, v93
	v_and_b32_e32 v227, 0xffff0000, v93
	v_lshlrev_b32_e32 v228, 16, v94
	v_and_b32_e32 v229, 0xffff0000, v94
	v_lshlrev_b32_e32 v230, 16, v95
	v_and_b32_e32 v231, 0xffff0000, v95
	v_pk_mul_f32 v[224:225], v[214:215], v[224:225]
	v_pk_mul_f32 v[226:227], v[214:215], v[226:227]
	v_pk_mul_f32 v[228:229], v[214:215], v[228:229]
	v_pk_mul_f32 v[230:231], v[214:215], v[230:231]
	v_pk_mul_f32 v[224:225], v[48:49], v[224:225]
	v_pk_mul_f32 v[226:227], v[50:51], v[226:227]
	v_pk_mul_f32 v[228:229], v[52:53], v[228:229]
	v_pk_mul_f32 v[230:231], v[54:55], v[230:231]
	global_store_dwordx4 v3, v[224:227], s[16:17] offset:2048
	global_store_dwordx4 v3, v[228:231], s[16:17] offset:2064
	v_lshlrev_b32_e32 v216, 16, v96
	v_and_b32_e32 v217, 0xffff0000, v96
	v_lshlrev_b32_e32 v218, 16, v97
	v_and_b32_e32 v219, 0xffff0000, v97
	v_lshlrev_b32_e32 v220, 16, v98
	v_and_b32_e32 v221, 0xffff0000, v98
	v_lshlrev_b32_e32 v222, 16, v99
	v_and_b32_e32 v223, 0xffff0000, v99
	v_pk_mul_f32 v[216:217], v[214:215], v[216:217]
	v_pk_mul_f32 v[218:219], v[214:215], v[218:219]
	v_pk_mul_f32 v[220:221], v[214:215], v[220:221]
	v_pk_mul_f32 v[222:223], v[214:215], v[222:223]
	v_pk_mul_f32 v[216:217], v[56:57], v[216:217]
	v_pk_mul_f32 v[218:219], v[58:59], v[218:219]
	v_pk_mul_f32 v[220:221], v[60:61], v[220:221]
	v_pk_mul_f32 v[222:223], v[62:63], v[222:223]
	global_store_dwordx4 v3, v[216:219], s[18:19] offset:0
	global_store_dwordx4 v3, v[220:223], s[18:19] offset:16
	v_lshlrev_b32_e32 v224, 16, v100
	v_and_b32_e32 v225, 0xffff0000, v100
	v_lshlrev_b32_e32 v226, 16, v101
	v_and_b32_e32 v227, 0xffff0000, v101
	v_lshlrev_b32_e32 v228, 16, v102
	v_and_b32_e32 v229, 0xffff0000, v102
	v_lshlrev_b32_e32 v230, 16, v103
	v_and_b32_e32 v231, 0xffff0000, v103
	v_pk_mul_f32 v[224:225], v[214:215], v[224:225]
	v_pk_mul_f32 v[226:227], v[214:215], v[226:227]
	v_pk_mul_f32 v[228:229], v[214:215], v[228:229]
	v_pk_mul_f32 v[230:231], v[214:215], v[230:231]
	v_pk_mul_f32 v[224:225], v[64:65], v[224:225]
	v_pk_mul_f32 v[226:227], v[66:67], v[226:227]
	v_pk_mul_f32 v[228:229], v[68:69], v[228:229]
	v_pk_mul_f32 v[230:231], v[70:71], v[230:231]
	global_store_dwordx4 v3, v[224:227], s[18:19] offset:2048
	global_store_dwordx4 v3, v[228:231], s[18:19] offset:2064
	s_mul_i32 s26, s74, 2
	s_add_i32 s26, s26, s52
	s_lshl_b32 s27, s26, 3
	s_add_u32 s8, s4, s27
	s_addc_u32 s9, s5, 0
	global_load_dwordx2 v[204:205], v232, s[8:9]
	s_lshl_b32 s27, s26, 13
	s_add_u32 s8, s6, s27
	s_addc_u32 s9, s7, 0
	s_add_u32 s10, s8, 0x1000
	s_addc_u32 s11, s9, 0
	global_load_dwordx4 v[136:139], v2, s[8:9] offset:0
	global_load_dwordx4 v[140:143], v2, s[8:9] offset:1024
	global_load_dwordx4 v[144:147], v2, s[8:9] offset:2048
	global_load_dwordx4 v[148:151], v2, s[8:9] offset:3072
	global_load_dwordx4 v[152:155], v2, s[10:11] offset:0
	global_load_dwordx4 v[156:159], v2, s[10:11] offset:1024
	global_load_dwordx4 v[160:163], v2, s[10:11] offset:2048
	global_load_dwordx4 v[164:167], v2, s[10:11] offset:3072
	s_mul_i32 s26, s74, 1
	s_add_i32 s26, s26, s52
	s_lshl_b32 s27, s26, 14
	s_add_u32 s12, s56, s27
	s_addc_u32 s13, s57, 0
	s_add_u32 s14, s12, 0x1000
	s_addc_u32 s15, s13, 0
	s_add_u32 s16, s14, 0x1000
	s_addc_u32 s17, s15, 0
	s_add_u32 s18, s16, 0x1000
	s_addc_u32 s19, s17, 0
	s_waitcnt vmcnt(25)
; __device__ __forceinline__ float bflo(unsigned w) { return __uint_as_float(w << 16); }
; __device__ __forceinline__ float bfhi(unsigned w) { return __uint_as_float(w & 0xffff0000u); }
; __device__ __forceinline__ void phase_final_norm(const bf16_t* Hb, const unsigned long long* ssq, const float* g, float* out, int gw, int ngw, int lane, float scale) {
;     for (int m = gw; m < MTOK; m += ngw) { const float rstd = scale / sqrtf((float)ssq[m] * (1.0f / 16777216.0f) * (1.0f / DM) + EPS);
;         const u32x4* xr = (const u32x4*)(Hb + (size_t)m * DM) + lane; f32x4* o = (f32x4*)(out + (size_t)m * DM); const f32x4* gr = (const f32x4*)g;
; #pragma unroll
;         for (int j = 0; j < 8; ++j) { const u32x4 r = xr[64 * j]; const int c4 = 2 * (64 * j + lane);
;             const f32x4 g0 = gr[c4], g1 = gr[c4 + 1];
;             o[c4] = (f32x4){bflo(r.x) * rstd * g0.x, bfhi(r.x) * rstd * g0.y, bflo(r.y) * rstd * g0.z, bfhi(r.y) * rstd * g0.w};
;             o[c4 + 1] = (f32x4){bflo(r.z) * rstd * g1.x, bfhi(r.z) * rstd * g1.y, bflo(r.w) * rstd * g1.z, bfhi(r.w) * rstd * g1.w}; } }
	v_ffbh_u32_e32 v208, v203
	v_min_u32_e32 v208, 32, v208
	v_lshlrev_b64 v[202:203], v208, v[202:203]
	v_min_u32_e32 v202, 1, v202
	v_or_b32_e32 v202, v203, v202
	v_cvt_f32_u32_e32 v202, v202
	v_sub_u32_e32 v208, 32, v208
	v_ldexp_f32 v208, v202, v208
	v_mul_f32_e32 v208, 0x33800000, v208
	v_fmamk_f32 v208, v208, 0x39800000, v233
	v_mul_f32_e32 v209, 0x4f800000, v208
	v_cmp_gt_f32_e32 vcc, s28, v208
	s_nop 1
	v_cndmask_b32_e32 v208, v208, v209, vcc
	v_sqrt_f32_e32 v209, v208
	s_nop 1
	v_add_u32_e32 v210, -1, v209
	v_add_u32_e32 v211, 1, v209
	v_fma_f32 v212, -v210, v209, v208
	v_fma_f32 v213, -v211, v209, v208
	v_cmp_ge_f32_e64 s[0:1], 0, v212
	s_nop 1
	v_cndmask_b32_e64 v209, v209, v210, s[0:1]
	v_cmp_lt_f32_e64 s[0:1], 0, v213
	s_nop 1
	v_cndmask_b32_e64 v209, v209, v211, s[0:1]
	v_mul_f32_e32 v210, 0x37800000, v209
	v_cndmask_b32_e32 v209, v209, v210, vcc
	v_cmp_class_f32_e32 vcc, v208, v234
	s_nop 1
	v_cndmask_b32_e32 v208, v209, v208, vcc
	v_div_scale_f32 v209, s[0:1], v208, v208, 1.0
	v_rcp_f32_e32 v211, v209
	v_div_scale_f32 v210, vcc, 1.0, v208, 1.0
	s_nop 0
	v_fma_f32 v212, -v209, v211, 1.0
	v_fmac_f32_e32 v211, v212, v211
	v_mul_f32_e32 v212, v210, v211
	v_fma_f32 v213, -v209, v212, v210
	v_fmac_f32_e32 v212, v213, v211
	v_fma_f32 v209, -v209, v212, v210
	s_nop 1
	v_div_fmas_f32 v209, v209, v211, v212
	v_div_fixup_f32 v214, v209, v208, 1.0
	v_mov_b32_e32 v215, v214
	v_lshlrev_b32_e32 v216, 16, v104
	v_and_b32_e32 v217, 0xffff0000, v104
	v_lshlrev_b32_e32 v218, 16, v105
	v_and_b32_e32 v219, 0xffff0000, v105
	v_lshlrev_b32_e32 v220, 16, v106
	v_and_b32_e32 v221, 0xffff0000, v106
	v_lshlrev_b32_e32 v222, 16, v107
	v_and_b32_e32 v223, 0xffff0000, v107
	v_pk_mul_f32 v[216:217], v[214:215], v[216:217]
	v_pk_mul_f32 v[218:219], v[214:215], v[218:219]
	v_pk_mul_f32 v[220:221], v[214:215], v[220:221]
	v_pk_mul_f32 v[222:223], v[214:215], v[222:223]
	v_pk_mul_f32 v[216:217], v[8:9], v[216:217]
	v_pk_mul_f32 v[218:219], v[10:11], v[218:219]
	v_pk_mul_f32 v[220:221], v[12:13], v[220:221]
	v_pk_mul_f32 v[222:223], v[14:15], v[222:223]
	global_store_dwordx4 v3, v[216:219], s[12:13] offset:0
	global_store_dwordx4 v3, v[220:223], s[12:13] offset:16
	v_lshlrev_b32_e32 v224, 16, v108
	v_and_b32_e32 v225, 0xffff0000, v108
	v_lshlrev_b32_e32 v226, 16, v109
	v_and_b32_e32 v227, 0xffff0000, v109
	v_lshlrev_b32_e32 v228, 16, v110
	v_and_b32_e32 v229, 0xffff0000, v110
	v_lshlrev_b32_e32 v230, 16, v111
	v_and_b32_e32 v231, 0xffff0000, v111
	v_pk_mul_f32 v[224:225], v[214:215], v[224:225]
	v_pk_mul_f32 v[226:227], v[214:215], v[226:227]
	v_pk_mul_f32 v[228:229], v[214:215], v[228:229]
	v_pk_mul_f32 v[230:231], v[214:215], v[230:231]
	v_pk_mul_f32 v[224:225], v[16:17], v[224:225]
	v_pk_mul_f32 v[226:227], v[18:19], v[226:227]
	v_pk_mul_f32 v[228:229], v[20:21], v[228:229]
	v_pk_mul_f32 v[230:231], v[22:23], v[230:231]
	global_store_dwordx4 v3, v[224:227], s[12:13] offset:2048
	global_store_dwordx4 v3, v[228:231], s[12:13] offset:2064
	v_lshlrev_b32_e32 v216, 16, v112
	v_and_b32_e32 v217, 0xffff0000, v112
	v_lshlrev_b32_e32 v218, 16, v113
	v_and_b32_e32 v219, 0xffff0000, v113
	v_lshlrev_b32_e32 v220, 16, v114
	v_and_b32_e32 v221, 0xffff0000, v114
	v_lshlrev_b32_e32 v222, 16, v115
	v_and_b32_e32 v223, 0xffff0000, v115
	v_pk_mul_f32 v[216:217], v[214:215], v[216:217]
	v_pk_mul_f32 v[218:219], v[214:215], v[218:219]
	v_pk_mul_f32 v[220:221], v[214:215], v[220:221]
	v_pk_mul_f32 v[222:223], v[214:215], v[222:223]
	v_pk_mul_f32 v[216:217], v[24:25], v[216:217]
	v_pk_mul_f32 v[218:219], v[26:27], v[218:219]
	v_pk_mul_f32 v[220:221], v[28:29], v[220:221]
	v_pk_mul_f32 v[222:223], v[30:31], v[222:223]
	global_store_dwordx4 v3, v[216:219], s[14:15] offset:0
	global_store_dwordx4 v3, v[220:223], s[14:15] offset:16
	v_lshlrev_b32_e32 v224, 16, v116
	v_and_b32_e32 v225, 0xffff0000, v116
	v_lshlrev_b32_e32 v226, 16, v117
	v_and_b32_e32 v227, 0xffff0000, v117
	v_lshlrev_b32_e32 v228, 16, v118
	v_and_b32_e32 v229, 0xffff0000, v118
	v_lshlrev_b32_e32 v230, 16, v119
	v_and_b32_e32 v231, 0xffff0000, v119
	v_pk_mul_f32 v[224:225], v[214:215], v[224:225]
	v_pk_mul_f32 v[226:227], v[214:215], v[226:227]
	v_pk_mul_f32 v[228:229], v[214:215], v[228:229]
	v_pk_mul_f32 v[230:231], v[214:215], v[230:231]
	v_pk_mul_f32 v[224:225], v[32:33], v[224:225]
	v_pk_mul_f32 v[226:227], v[34:35], v[226:227]
	v_pk_mul_f32 v[228:229], v[36:37], v[228:229]
	v_pk_mul_f32 v[230:231], v[38:39], v[230:231]
	global_store_dwordx4 v3, v[224:227], s[14:15] offset:2048
	global_store_dwordx4 v3, v[228:231], s[14:15] offset:2064
	v_lshlrev_b32_e32 v216, 16, v120
	v_and_b32_e32 v217, 0xffff0000, v120
	v_lshlrev_b32_e32 v218, 16, v121
	v_and_b32_e32 v219, 0xffff0000, v121
	v_lshlrev_b32_e32 v220, 16, v122
	v_and_b32_e32 v221, 0xffff0000, v122
	v_lshlrev_b32_e32 v222, 16, v123
	v_and_b32_e32 v223, 0xffff0000, v123
	v_pk_mul_f32 v[216:217], v[214:215], v[216:217]
	v_pk_mul_f32 v[218:219], v[214:215], v[218:219]
	v_pk_mul_f32 v[220:221], v[214:215], v[220:221]
	v_pk_mul_f32 v[222:223], v[214:215], v[222:223]
	v_pk_mul_f32 v[216:217], v[40:41], v[216:217]
	v_pk_mul_f32 v[218:219], v[42:43], v[218:219]
	v_pk_mul_f32 v[220:221], v[44:45], v[220:221]
	v_pk_mul_f32 v[222:223], v[46:47], v[222:223]
	global_store_dwordx4 v3, v[216:219], s[16:17] offset:0
	global_store_dwordx4 v3, v[220:223], s[16:17] offset:16
	v_lshlrev_b32_e32 v224, 16, v124
	v_and_b32_e32 v225, 0xffff0000, v124
	v_lshlrev_b32_e32 v226, 16, v125
	v_and_b32_e32 v227, 0xffff0000, v125
	v_lshlrev_b32_e32 v228, 16, v126
	v_and_b32_e32 v229, 0xffff0000, v126
	v_lshlrev_b32_e32 v230, 16, v127
	v_and_b32_e32 v231, 0xffff0000, v127
; __device__ __forceinline__ float bflo(unsigned w) { return __uint_as_float(w << 16); }
; __device__ __forceinline__ float bfhi(unsigned w) { return __uint_as_float(w & 0xffff0000u); }
; __device__ __forceinline__ void phase_final_norm(const bf16_t* Hb, const unsigned long long* ssq, const float* g, float* out, int gw, int ngw, int lane, float scale) {
;     for (int m = gw; m < MTOK; m += ngw) { const float rstd = scale / sqrtf((float)ssq[m] * (1.0f / 16777216.0f) * (1.0f / DM) + EPS);
;         const u32x4* xr = (const u32x4*)(Hb + (size_t)m * DM) + lane; f32x4* o = (f32x4*)(out + (size_t)m * DM); const f32x4* gr = (const f32x4*)g;
; #pragma unroll
;         for (int j = 0; j < 8; ++j) { const u32x4 r = xr[64 * j]; const int c4 = 2 * (64 * j + lane);
;             const f32x4 g0 = gr[c4], g1 = gr[c4 + 1];
;             o[c4] = (f32x4){bflo(r.x) * rstd * g0.x, bfhi(r.x) * rstd * g0.y, bflo(r.y) * rstd * g0.z, bfhi(r.y) * rstd * g0.w};
;             o[c4 + 1] = (f32x4){bflo(r.z) * rstd * g1.x, bfhi(r.z) * rstd * g1.y, bflo(r.w) * rstd * g1.z, bfhi(r.w) * rstd * g1.w}; } }
	v_pk_mul_f32 v[224:225], v[214:215], v[224:225]
	v_pk_mul_f32 v[226:227], v[214:215], v[226:227]
	v_pk_mul_f32 v[228:229], v[214:215], v[228:229]
	v_pk_mul_f32 v[230:231], v[214:215], v[230:231]
	v_pk_mul_f32 v[224:225], v[48:49], v[224:225]
	v_pk_mul_f32 v[226:227], v[50:51], v[226:227]
	v_pk_mul_f32 v[228:229], v[52:53], v[228:229]
	v_pk_mul_f32 v[230:231], v[54:55], v[230:231]
	global_store_dwordx4 v3, v[224:227], s[16:17] offset:2048
	global_store_dwordx4 v3, v[228:231], s[16:17] offset:2064
	v_lshlrev_b32_e32 v216, 16, v128
	v_and_b32_e32 v217, 0xffff0000, v128
	v_lshlrev_b32_e32 v218, 16, v129
	v_and_b32_e32 v219, 0xffff0000, v129
	v_lshlrev_b32_e32 v220, 16, v130
	v_and_b32_e32 v221, 0xffff0000, v130
	v_lshlrev_b32_e32 v222, 16, v131
	v_and_b32_e32 v223, 0xffff0000, v131
	v_pk_mul_f32 v[216:217], v[214:215], v[216:217]
	v_pk_mul_f32 v[218:219], v[214:215], v[218:219]
	v_pk_mul_f32 v[220:221], v[214:215], v[220:221]
	v_pk_mul_f32 v[222:223], v[214:215], v[222:223]
	v_pk_mul_f32 v[216:217], v[56:57], v[216:217]
	v_pk_mul_f32 v[218:219], v[58:59], v[218:219]
	v_pk_mul_f32 v[220:221], v[60:61], v[220:221]
	v_pk_mul_f32 v[222:223], v[62:63], v[222:223]
	global_store_dwordx4 v3, v[216:219], s[18:19] offset:0
	global_store_dwordx4 v3, v[220:223], s[18:19] offset:16
	v_lshlrev_b32_e32 v224, 16, v132
	v_and_b32_e32 v225, 0xffff0000, v132
	v_lshlrev_b32_e32 v226, 16, v133
	v_and_b32_e32 v227, 0xffff0000, v133
	v_lshlrev_b32_e32 v228, 16, v134
	v_and_b32_e32 v229, 0xffff0000, v134
	v_lshlrev_b32_e32 v230, 16, v135
	v_and_b32_e32 v231, 0xffff0000, v135
	v_pk_mul_f32 v[224:225], v[214:215], v[224:225]
	v_pk_mul_f32 v[226:227], v[214:215], v[226:227]
	v_pk_mul_f32 v[228:229], v[214:215], v[228:229]
	v_pk_mul_f32 v[230:231], v[214:215], v[230:231]
	v_pk_mul_f32 v[224:225], v[64:65], v[224:225]
	v_pk_mul_f32 v[226:227], v[66:67], v[226:227]
	v_pk_mul_f32 v[228:229], v[68:69], v[228:229]
	v_pk_mul_f32 v[230:231], v[70:71], v[230:231]
	global_store_dwordx4 v3, v[224:227], s[18:19] offset:2048
	global_store_dwordx4 v3, v[228:231], s[18:19] offset:2064
	s_mul_i32 s26, s74, 3
	s_add_i32 s26, s26, s52
	s_lshl_b32 s27, s26, 3
	s_add_u32 s8, s4, s27
	s_addc_u32 s9, s5, 0
	global_load_dwordx2 v[206:207], v232, s[8:9]
	s_lshl_b32 s27, s26, 13
	s_add_u32 s8, s6, s27
	s_addc_u32 s9, s7, 0
	s_add_u32 s10, s8, 0x1000
	s_addc_u32 s11, s9, 0
	global_load_dwordx4 v[168:171], v2, s[8:9] offset:0
	global_load_dwordx4 v[172:175], v2, s[8:9] offset:1024
	global_load_dwordx4 v[176:179], v2, s[8:9] offset:2048
	global_load_dwordx4 v[180:183], v2, s[8:9] offset:3072
	global_load_dwordx4 v[184:187], v2, s[10:11] offset:0
	global_load_dwordx4 v[188:191], v2, s[10:11] offset:1024
	global_load_dwordx4 v[192:195], v2, s[10:11] offset:2048
	global_load_dwordx4 v[196:199], v2, s[10:11] offset:3072
	s_mul_i32 s26, s74, 2
	s_add_i32 s26, s26, s52
	s_lshl_b32 s27, s26, 14
	s_add_u32 s12, s56, s27
	s_addc_u32 s13, s57, 0
	s_add_u32 s14, s12, 0x1000
	s_addc_u32 s15, s13, 0
	s_add_u32 s16, s14, 0x1000
	s_addc_u32 s17, s15, 0
	s_add_u32 s18, s16, 0x1000
	s_addc_u32 s19, s17, 0
	s_waitcnt vmcnt(25)
	v_ffbh_u32_e32 v208, v205
	v_min_u32_e32 v208, 32, v208
	v_lshlrev_b64 v[204:205], v208, v[204:205]
	v_min_u32_e32 v204, 1, v204
	v_or_b32_e32 v204, v205, v204
	v_cvt_f32_u32_e32 v204, v204
	v_sub_u32_e32 v208, 32, v208
	v_ldexp_f32 v208, v204, v208
	v_mul_f32_e32 v208, 0x33800000, v208
	v_fmamk_f32 v208, v208, 0x39800000, v233
	v_mul_f32_e32 v209, 0x4f800000, v208
	v_cmp_gt_f32_e32 vcc, s28, v208
	s_nop 1
	v_cndmask_b32_e32 v208, v208, v209, vcc
	v_sqrt_f32_e32 v209, v208
	s_nop 1
	v_add_u32_e32 v210, -1, v209
	v_add_u32_e32 v211, 1, v209
	v_fma_f32 v212, -v210, v209, v208
	v_fma_f32 v213, -v211, v209, v208
	v_cmp_ge_f32_e64 s[0:1], 0, v212
	s_nop 1
	v_cndmask_b32_e64 v209, v209, v210, s[0:1]
	v_cmp_lt_f32_e64 s[0:1], 0, v213
	s_nop 1
	v_cndmask_b32_e64 v209, v209, v211, s[0:1]
	v_mul_f32_e32 v210, 0x37800000, v209
	v_cndmask_b32_e32 v209, v209, v210, vcc
	v_cmp_class_f32_e32 vcc, v208, v234
	s_nop 1
	v_cndmask_b32_e32 v208, v209, v208, vcc
	v_div_scale_f32 v209, s[0:1], v208, v208, 1.0
	v_rcp_f32_e32 v211, v209
	v_div_scale_f32 v210, vcc, 1.0, v208, 1.0
	s_nop 0
	v_fma_f32 v212, -v209, v211, 1.0
	v_fmac_f32_e32 v211, v212, v211
	v_mul_f32_e32 v212, v210, v211
	v_fma_f32 v213, -v209, v212, v210
	v_fmac_f32_e32 v212, v213, v211
	v_fma_f32 v209, -v209, v212, v210
	s_nop 1
	v_div_fmas_f32 v209, v209, v211, v212
	v_div_fixup_f32 v214, v209, v208, 1.0
	v_mov_b32_e32 v215, v214
	v_lshlrev_b32_e32 v216, 16, v136
	v_and_b32_e32 v217, 0xffff0000, v136
	v_lshlrev_b32_e32 v218, 16, v137
	v_and_b32_e32 v219, 0xffff0000, v137
	v_lshlrev_b32_e32 v220, 16, v138
	v_and_b32_e32 v221, 0xffff0000, v138
	v_lshlrev_b32_e32 v222, 16, v139
	v_and_b32_e32 v223, 0xffff0000, v139
	v_pk_mul_f32 v[216:217], v[214:215], v[216:217]
	v_pk_mul_f32 v[218:219], v[214:215], v[218:219]
	v_pk_mul_f32 v[220:221], v[214:215], v[220:221]
	v_pk_mul_f32 v[222:223], v[214:215], v[222:223]
	v_pk_mul_f32 v[216:217], v[8:9], v[216:217]
	v_pk_mul_f32 v[218:219], v[10:11], v[218:219]
	v_pk_mul_f32 v[220:221], v[12:13], v[220:221]
	v_pk_mul_f32 v[222:223], v[14:15], v[222:223]
	global_store_dwordx4 v3, v[216:219], s[12:13] offset:0
	global_store_dwordx4 v3, v[220:223], s[12:13] offset:16
	v_lshlrev_b32_e32 v224, 16, v140
	v_and_b32_e32 v225, 0xffff0000, v140
	v_lshlrev_b32_e32 v226, 16, v141
	v_and_b32_e32 v227, 0xffff0000, v141
	v_lshlrev_b32_e32 v228, 16, v142
	v_and_b32_e32 v229, 0xffff0000, v142
	v_lshlrev_b32_e32 v230, 16, v143
	v_and_b32_e32 v231, 0xffff0000, v143
	v_pk_mul_f32 v[224:225], v[214:215], v[224:225]
; __device__ __forceinline__ float bflo(unsigned w) { return __uint_as_float(w << 16); }
; __device__ __forceinline__ float bfhi(unsigned w) { return __uint_as_float(w & 0xffff0000u); }
; __device__ __forceinline__ void phase_final_norm(const bf16_t* Hb, const unsigned long long* ssq, const float* g, float* out, int gw, int ngw, int lane, float scale) {
;     for (int m = gw; m < MTOK; m += ngw) { const float rstd = scale / sqrtf((float)ssq[m] * (1.0f / 16777216.0f) * (1.0f / DM) + EPS);
;         const u32x4* xr = (const u32x4*)(Hb + (size_t)m * DM) + lane; f32x4* o = (f32x4*)(out + (size_t)m * DM); const f32x4* gr = (const f32x4*)g;
; #pragma unroll
;         for (int j = 0; j < 8; ++j) { const u32x4 r = xr[64 * j]; const int c4 = 2 * (64 * j + lane);
;             const f32x4 g0 = gr[c4], g1 = gr[c4 + 1];
;             o[c4] = (f32x4){bflo(r.x) * rstd * g0.x, bfhi(r.x) * rstd * g0.y, bflo(r.y) * rstd * g0.z, bfhi(r.y) * rstd * g0.w};
;             o[c4 + 1] = (f32x4){bflo(r.z) * rstd * g1.x, bfhi(r.z) * rstd * g1.y, bflo(r.w) * rstd * g1.z, bfhi(r.w) * rstd * g1.w}; } }
	v_pk_mul_f32 v[226:227], v[214:215], v[226:227]
	v_pk_mul_f32 v[228:229], v[214:215], v[228:229]
	v_pk_mul_f32 v[230:231], v[214:215], v[230:231]
	v_pk_mul_f32 v[224:225], v[16:17], v[224:225]
	v_pk_mul_f32 v[226:227], v[18:19], v[226:227]
	v_pk_mul_f32 v[228:229], v[20:21], v[228:229]
	v_pk_mul_f32 v[230:231], v[22:23], v[230:231]
	global_store_dwordx4 v3, v[224:227], s[12:13] offset:2048
	global_store_dwordx4 v3, v[228:231], s[12:13] offset:2064
	v_lshlrev_b32_e32 v216, 16, v144
	v_and_b32_e32 v217, 0xffff0000, v144
	v_lshlrev_b32_e32 v218, 16, v145
	v_and_b32_e32 v219, 0xffff0000, v145
	v_lshlrev_b32_e32 v220, 16, v146
	v_and_b32_e32 v221, 0xffff0000, v146
	v_lshlrev_b32_e32 v222, 16, v147
	v_and_b32_e32 v223, 0xffff0000, v147
	v_pk_mul_f32 v[216:217], v[214:215], v[216:217]
	v_pk_mul_f32 v[218:219], v[214:215], v[218:219]
	v_pk_mul_f32 v[220:221], v[214:215], v[220:221]
	v_pk_mul_f32 v[222:223], v[214:215], v[222:223]
	v_pk_mul_f32 v[216:217], v[24:25], v[216:217]
	v_pk_mul_f32 v[218:219], v[26:27], v[218:219]
	v_pk_mul_f32 v[220:221], v[28:29], v[220:221]
	v_pk_mul_f32 v[222:223], v[30:31], v[222:223]
	global_store_dwordx4 v3, v[216:219], s[14:15] offset:0
	global_store_dwordx4 v3, v[220:223], s[14:15] offset:16
	v_lshlrev_b32_e32 v224, 16, v148
	v_and_b32_e32 v225, 0xffff0000, v148
	v_lshlrev_b32_e32 v226, 16, v149
	v_and_b32_e32 v227, 0xffff0000, v149
	v_lshlrev_b32_e32 v228, 16, v150
	v_and_b32_e32 v229, 0xffff0000, v150
	v_lshlrev_b32_e32 v230, 16, v151
	v_and_b32_e32 v231, 0xffff0000, v151
	v_pk_mul_f32 v[224:225], v[214:215], v[224:225]
	v_pk_mul_f32 v[226:227], v[214:215], v[226:227]
	v_pk_mul_f32 v[228:229], v[214:215], v[228:229]
	v_pk_mul_f32 v[230:231], v[214:215], v[230:231]
	v_pk_mul_f32 v[224:225], v[32:33], v[224:225]
	v_pk_mul_f32 v[226:227], v[34:35], v[226:227]
	v_pk_mul_f32 v[228:229], v[36:37], v[228:229]
	v_pk_mul_f32 v[230:231], v[38:39], v[230:231]
	global_store_dwordx4 v3, v[224:227], s[14:15] offset:2048
	global_store_dwordx4 v3, v[228:231], s[14:15] offset:2064
	v_lshlrev_b32_e32 v216, 16, v152
	v_and_b32_e32 v217, 0xffff0000, v152
	v_lshlrev_b32_e32 v218, 16, v153
	v_and_b32_e32 v219, 0xffff0000, v153
	v_lshlrev_b32_e32 v220, 16, v154
	v_and_b32_e32 v221, 0xffff0000, v154
	v_lshlrev_b32_e32 v222, 16, v155
	v_and_b32_e32 v223, 0xffff0000, v155
	v_pk_mul_f32 v[216:217], v[214:215], v[216:217]
	v_pk_mul_f32 v[218:219], v[214:215], v[218:219]
	v_pk_mul_f32 v[220:221], v[214:215], v[220:221]
	v_pk_mul_f32 v[222:223], v[214:215], v[222:223]
	v_pk_mul_f32 v[216:217], v[40:41], v[216:217]
	v_pk_mul_f32 v[218:219], v[42:43], v[218:219]
	v_pk_mul_f32 v[220:221], v[44:45], v[220:221]
	v_pk_mul_f32 v[222:223], v[46:47], v[222:223]
	global_store_dwordx4 v3, v[216:219], s[16:17] offset:0
	global_store_dwordx4 v3, v[220:223], s[16:17] offset:16
	v_lshlrev_b32_e32 v224, 16, v156
	v_and_b32_e32 v225, 0xffff0000, v156
	v_lshlrev_b32_e32 v226, 16, v157
	v_and_b32_e32 v227, 0xffff0000, v157
	v_lshlrev_b32_e32 v228, 16, v158
	v_and_b32_e32 v229, 0xffff0000, v158
	v_lshlrev_b32_e32 v230, 16, v159
	v_and_b32_e32 v231, 0xffff0000, v159
	v_pk_mul_f32 v[224:225], v[214:215], v[224:225]
	v_pk_mul_f32 v[226:227], v[214:215], v[226:227]
	v_pk_mul_f32 v[228:229], v[214:215], v[228:229]
	v_pk_mul_f32 v[230:231], v[214:215], v[230:231]
	v_pk_mul_f32 v[224:225], v[48:49], v[224:225]
	v_pk_mul_f32 v[226:227], v[50:51], v[226:227]
	v_pk_mul_f32 v[228:229], v[52:53], v[228:229]
	v_pk_mul_f32 v[230:231], v[54:55], v[230:231]
	global_store_dwordx4 v3, v[224:227], s[16:17] offset:2048
	global_store_dwordx4 v3, v[228:231], s[16:17] offset:2064
	v_lshlrev_b32_e32 v216, 16, v160
	v_and_b32_e32 v217, 0xffff0000, v160
	v_lshlrev_b32_e32 v218, 16, v161
	v_and_b32_e32 v219, 0xffff0000, v161
	v_lshlrev_b32_e32 v220, 16, v162
	v_and_b32_e32 v221, 0xffff0000, v162
	v_lshlrev_b32_e32 v222, 16, v163
	v_and_b32_e32 v223, 0xffff0000, v163
	v_pk_mul_f32 v[216:217], v[214:215], v[216:217]
	v_pk_mul_f32 v[218:219], v[214:215], v[218:219]
	v_pk_mul_f32 v[220:221], v[214:215], v[220:221]
	v_pk_mul_f32 v[222:223], v[214:215], v[222:223]
	v_pk_mul_f32 v[216:217], v[56:57], v[216:217]
	v_pk_mul_f32 v[218:219], v[58:59], v[218:219]
	v_pk_mul_f32 v[220:221], v[60:61], v[220:221]
	v_pk_mul_f32 v[222:223], v[62:63], v[222:223]
	global_store_dwordx4 v3, v[216:219], s[18:19] offset:0
	global_store_dwordx4 v3, v[220:223], s[18:19] offset:16
	v_lshlrev_b32_e32 v224, 16, v164
	v_and_b32_e32 v225, 0xffff0000, v164
	v_lshlrev_b32_e32 v226, 16, v165
	v_and_b32_e32 v227, 0xffff0000, v165
	v_lshlrev_b32_e32 v228, 16, v166
	v_and_b32_e32 v229, 0xffff0000, v166
	v_lshlrev_b32_e32 v230, 16, v167
	v_and_b32_e32 v231, 0xffff0000, v167
	v_pk_mul_f32 v[224:225], v[214:215], v[224:225]
	v_pk_mul_f32 v[226:227], v[214:215], v[226:227]
	v_pk_mul_f32 v[228:229], v[214:215], v[228:229]
	v_pk_mul_f32 v[230:231], v[214:215], v[230:231]
	v_pk_mul_f32 v[224:225], v[64:65], v[224:225]
	v_pk_mul_f32 v[226:227], v[66:67], v[226:227]
	v_pk_mul_f32 v[228:229], v[68:69], v[228:229]
	v_pk_mul_f32 v[230:231], v[70:71], v[230:231]
	global_store_dwordx4 v3, v[224:227], s[18:19] offset:2048
	global_store_dwordx4 v3, v[228:231], s[18:19] offset:2064
	s_mul_i32 s26, s74, 3
	s_add_i32 s26, s26, s52
	s_lshl_b32 s27, s26, 14
	s_add_u32 s12, s56, s27
	s_addc_u32 s13, s57, 0
	s_add_u32 s14, s12, 0x1000
	s_addc_u32 s15, s13, 0
	s_add_u32 s16, s14, 0x1000
	s_addc_u32 s17, s15, 0
	s_add_u32 s18, s16, 0x1000
	s_addc_u32 s19, s17, 0
	s_waitcnt vmcnt(16)
; __device__ __forceinline__ float bflo(unsigned w) { return __uint_as_float(w << 16); }
; __device__ __forceinline__ float bfhi(unsigned w) { return __uint_as_float(w & 0xffff0000u); }
; __device__ __forceinline__ void phase_final_norm(const bf16_t* Hb, const unsigned long long* ssq, const float* g, float* out, int gw, int ngw, int lane, float scale) {
;     for (int m = gw; m < MTOK; m += ngw) { const float rstd = scale / sqrtf((float)ssq[m] * (1.0f / 16777216.0f) * (1.0f / DM) + EPS);
;         const u32x4* xr = (const u32x4*)(Hb + (size_t)m * DM) + lane; f32x4* o = (f32x4*)(out + (size_t)m * DM); const f32x4* gr = (const f32x4*)g;
; #pragma unroll
;         for (int j = 0; j < 8; ++j) { const u32x4 r = xr[64 * j]; const int c4 = 2 * (64 * j + lane);
;             const f32x4 g0 = gr[c4], g1 = gr[c4 + 1];
;             o[c4] = (f32x4){bflo(r.x) * rstd * g0.x, bfhi(r.x) * rstd * g0.y, bflo(r.y) * rstd * g0.z, bfhi(r.y) * rstd * g0.w};
;             o[c4 + 1] = (f32x4){bflo(r.z) * rstd * g1.x, bfhi(r.z) * rstd * g1.y, bflo(r.w) * rstd * g1.z, bfhi(r.w) * rstd * g1.w}; } }
	v_ffbh_u32_e32 v208, v207
	v_min_u32_e32 v208, 32, v208
	v_lshlrev_b64 v[206:207], v208, v[206:207]
	v_min_u32_e32 v206, 1, v206
	v_or_b32_e32 v206, v207, v206
	v_cvt_f32_u32_e32 v206, v206
	v_sub_u32_e32 v208, 32, v208
	v_ldexp_f32 v208, v206, v208
	v_mul_f32_e32 v208, 0x33800000, v208
	v_fmamk_f32 v208, v208, 0x39800000, v233
	v_mul_f32_e32 v209, 0x4f800000, v208
	v_cmp_gt_f32_e32 vcc, s28, v208
	s_nop 1
	v_cndmask_b32_e32 v208, v208, v209, vcc
	v_sqrt_f32_e32 v209, v208
	s_nop 1
	v_add_u32_e32 v210, -1, v209
	v_add_u32_e32 v211, 1, v209
	v_fma_f32 v212, -v210, v209, v208
	v_fma_f32 v213, -v211, v209, v208
	v_cmp_ge_f32_e64 s[0:1], 0, v212
	s_nop 1
	v_cndmask_b32_e64 v209, v209, v210, s[0:1]
	v_cmp_lt_f32_e64 s[0:1], 0, v213
	s_nop 1
	v_cndmask_b32_e64 v209, v209, v211, s[0:1]
	v_mul_f32_e32 v210, 0x37800000, v209
	v_cndmask_b32_e32 v209, v209, v210, vcc
	v_cmp_class_f32_e32 vcc, v208, v234
	s_nop 1
	v_cndmask_b32_e32 v208, v209, v208, vcc
	v_div_scale_f32 v209, s[0:1], v208, v208, 1.0
	v_rcp_f32_e32 v211, v209
	v_div_scale_f32 v210, vcc, 1.0, v208, 1.0
	s_nop 0
	v_fma_f32 v212, -v209, v211, 1.0
	v_fmac_f32_e32 v211, v212, v211
	v_mul_f32_e32 v212, v210, v211
	v_fma_f32 v213, -v209, v212, v210
	v_fmac_f32_e32 v212, v213, v211
	v_fma_f32 v209, -v209, v212, v210
	s_nop 1
	v_div_fmas_f32 v209, v209, v211, v212
	v_div_fixup_f32 v214, v209, v208, 1.0
	v_mov_b32_e32 v215, v214
	v_lshlrev_b32_e32 v216, 16, v168
	v_and_b32_e32 v217, 0xffff0000, v168
	v_lshlrev_b32_e32 v218, 16, v169
	v_and_b32_e32 v219, 0xffff0000, v169
	v_lshlrev_b32_e32 v220, 16, v170
	v_and_b32_e32 v221, 0xffff0000, v170
	v_lshlrev_b32_e32 v222, 16, v171
	v_and_b32_e32 v223, 0xffff0000, v171
	v_pk_mul_f32 v[216:217], v[214:215], v[216:217]
	v_pk_mul_f32 v[218:219], v[214:215], v[218:219]
	v_pk_mul_f32 v[220:221], v[214:215], v[220:221]
	v_pk_mul_f32 v[222:223], v[214:215], v[222:223]
	v_pk_mul_f32 v[216:217], v[8:9], v[216:217]
	v_pk_mul_f32 v[218:219], v[10:11], v[218:219]
	v_pk_mul_f32 v[220:221], v[12:13], v[220:221]
	v_pk_mul_f32 v[222:223], v[14:15], v[222:223]
	global_store_dwordx4 v3, v[216:219], s[12:13] offset:0
	global_store_dwordx4 v3, v[220:223], s[12:13] offset:16
	v_lshlrev_b32_e32 v224, 16, v172
	v_and_b32_e32 v225, 0xffff0000, v172
	v_lshlrev_b32_e32 v226, 16, v173
	v_and_b32_e32 v227, 0xffff0000, v173
	v_lshlrev_b32_e32 v228, 16, v174
	v_and_b32_e32 v229, 0xffff0000, v174
	v_lshlrev_b32_e32 v230, 16, v175
	v_and_b32_e32 v231, 0xffff0000, v175
	v_pk_mul_f32 v[224:225], v[214:215], v[224:225]
	v_pk_mul_f32 v[226:227], v[214:215], v[226:227]
	v_pk_mul_f32 v[228:229], v[214:215], v[228:229]
	v_pk_mul_f32 v[230:231], v[214:215], v[230:231]
	v_pk_mul_f32 v[224:225], v[16:17], v[224:225]
	v_pk_mul_f32 v[226:227], v[18:19], v[226:227]
	v_pk_mul_f32 v[228:229], v[20:21], v[228:229]
	v_pk_mul_f32 v[230:231], v[22:23], v[230:231]
	global_store_dwordx4 v3, v[224:227], s[12:13] offset:2048
	global_store_dwordx4 v3, v[228:231], s[12:13] offset:2064
	v_lshlrev_b32_e32 v216, 16, v176
	v_and_b32_e32 v217, 0xffff0000, v176
	v_lshlrev_b32_e32 v218, 16, v177
	v_and_b32_e32 v219, 0xffff0000, v177
	v_lshlrev_b32_e32 v220, 16, v178
	v_and_b32_e32 v221, 0xffff0000, v178
	v_lshlrev_b32_e32 v222, 16, v179
	v_and_b32_e32 v223, 0xffff0000, v179
	v_pk_mul_f32 v[216:217], v[214:215], v[216:217]
	v_pk_mul_f32 v[218:219], v[214:215], v[218:219]
	v_pk_mul_f32 v[220:221], v[214:215], v[220:221]
	v_pk_mul_f32 v[222:223], v[214:215], v[222:223]
	v_pk_mul_f32 v[216:217], v[24:25], v[216:217]
	v_pk_mul_f32 v[218:219], v[26:27], v[218:219]
	v_pk_mul_f32 v[220:221], v[28:29], v[220:221]
	v_pk_mul_f32 v[222:223], v[30:31], v[222:223]
	global_store_dwordx4 v3, v[216:219], s[14:15] offset:0
	global_store_dwordx4 v3, v[220:223], s[14:15] offset:16
	v_lshlrev_b32_e32 v224, 16, v180
	v_and_b32_e32 v225, 0xffff0000, v180
	v_lshlrev_b32_e32 v226, 16, v181
; __device__ __forceinline__ float bflo(unsigned w) { return __uint_as_float(w << 16); }
; __device__ __forceinline__ float bfhi(unsigned w) { return __uint_as_float(w & 0xffff0000u); }
; __device__ __forceinline__ void phase_final_norm(const bf16_t* Hb, const unsigned long long* ssq, const float* g, float* out, int gw, int ngw, int lane, float scale) {
;     for (int m = gw; m < MTOK; m += ngw) { const float rstd = scale / sqrtf((float)ssq[m] * (1.0f / 16777216.0f) * (1.0f / DM) + EPS);
;         const u32x4* xr = (const u32x4*)(Hb + (size_t)m * DM) + lane; f32x4* o = (f32x4*)(out + (size_t)m * DM); const f32x4* gr = (const f32x4*)g;
; #pragma unroll
;         for (int j = 0; j < 8; ++j) { const u32x4 r = xr[64 * j]; const int c4 = 2 * (64 * j + lane);
;             const f32x4 g0 = gr[c4], g1 = gr[c4 + 1];
;             o[c4] = (f32x4){bflo(r.x) * rstd * g0.x, bfhi(r.x) * rstd * g0.y, bflo(r.y) * rstd * g0.z, bfhi(r.y) * rstd * g0.w};
;             o[c4 + 1] = (f32x4){bflo(r.z) * rstd * g1.x, bfhi(r.z) * rstd * g1.y, bflo(r.w) * rstd * g1.z, bfhi(r.w) * rstd * g1.w}; } }
	v_and_b32_e32 v227, 0xffff0000, v181
	v_lshlrev_b32_e32 v228, 16, v182
	v_and_b32_e32 v229, 0xffff0000, v182
	v_lshlrev_b32_e32 v230, 16, v183
	v_and_b32_e32 v231, 0xffff0000, v183
	v_pk_mul_f32 v[224:225], v[214:215], v[224:225]
	v_pk_mul_f32 v[226:227], v[214:215], v[226:227]
	v_pk_mul_f32 v[228:229], v[214:215], v[228:229]
	v_pk_mul_f32 v[230:231], v[214:215], v[230:231]
	v_pk_mul_f32 v[224:225], v[32:33], v[224:225]
	v_pk_mul_f32 v[226:227], v[34:35], v[226:227]
	v_pk_mul_f32 v[228:229], v[36:37], v[228:229]
	v_pk_mul_f32 v[230:231], v[38:39], v[230:231]
	global_store_dwordx4 v3, v[224:227], s[14:15] offset:2048
	global_store_dwordx4 v3, v[228:231], s[14:15] offset:2064
	v_lshlrev_b32_e32 v216, 16, v184
	v_and_b32_e32 v217, 0xffff0000, v184
	v_lshlrev_b32_e32 v218, 16, v185
	v_and_b32_e32 v219, 0xffff0000, v185
	v_lshlrev_b32_e32 v220, 16, v186
	v_and_b32_e32 v221, 0xffff0000, v186
	v_lshlrev_b32_e32 v222, 16, v187
	v_and_b32_e32 v223, 0xffff0000, v187
	v_pk_mul_f32 v[216:217], v[214:215], v[216:217]
	v_pk_mul_f32 v[218:219], v[214:215], v[218:219]
	v_pk_mul_f32 v[220:221], v[214:215], v[220:221]
	v_pk_mul_f32 v[222:223], v[214:215], v[222:223]
	v_pk_mul_f32 v[216:217], v[40:41], v[216:217]
	v_pk_mul_f32 v[218:219], v[42:43], v[218:219]
	v_pk_mul_f32 v[220:221], v[44:45], v[220:221]
	v_pk_mul_f32 v[222:223], v[46:47], v[222:223]
	global_store_dwordx4 v3, v[216:219], s[16:17] offset:0
	global_store_dwordx4 v3, v[220:223], s[16:17] offset:16
	v_lshlrev_b32_e32 v224, 16, v188
	v_and_b32_e32 v225, 0xffff0000, v188
	v_lshlrev_b32_e32 v226, 16, v189
	v_and_b32_e32 v227, 0xffff0000, v189
	v_lshlrev_b32_e32 v228, 16, v190
	v_and_b32_e32 v229, 0xffff0000, v190
	v_lshlrev_b32_e32 v230, 16, v191
	v_and_b32_e32 v231, 0xffff0000, v191
	v_pk_mul_f32 v[224:225], v[214:215], v[224:225]
	v_pk_mul_f32 v[226:227], v[214:215], v[226:227]
	v_pk_mul_f32 v[228:229], v[214:215], v[228:229]
	v_pk_mul_f32 v[230:231], v[214:215], v[230:231]
	v_pk_mul_f32 v[224:225], v[48:49], v[224:225]
	v_pk_mul_f32 v[226:227], v[50:51], v[226:227]
	v_pk_mul_f32 v[228:229], v[52:53], v[228:229]
	v_pk_mul_f32 v[230:231], v[54:55], v[230:231]
	global_store_dwordx4 v3, v[224:227], s[16:17] offset:2048
	global_store_dwordx4 v3, v[228:231], s[16:17] offset:2064
	v_lshlrev_b32_e32 v216, 16, v192
	v_and_b32_e32 v217, 0xffff0000, v192
	v_lshlrev_b32_e32 v218, 16, v193
	v_and_b32_e32 v219, 0xffff0000, v193
	v_lshlrev_b32_e32 v220, 16, v194
	v_and_b32_e32 v221, 0xffff0000, v194
	v_lshlrev_b32_e32 v222, 16, v195
	v_and_b32_e32 v223, 0xffff0000, v195
	v_pk_mul_f32 v[216:217], v[214:215], v[216:217]
	v_pk_mul_f32 v[218:219], v[214:215], v[218:219]
	v_pk_mul_f32 v[220:221], v[214:215], v[220:221]
	v_pk_mul_f32 v[222:223], v[214:215], v[222:223]
	v_pk_mul_f32 v[216:217], v[56:57], v[216:217]
	v_pk_mul_f32 v[218:219], v[58:59], v[218:219]
	v_pk_mul_f32 v[220:221], v[60:61], v[220:221]
	v_pk_mul_f32 v[222:223], v[62:63], v[222:223]
	global_store_dwordx4 v3, v[216:219], s[18:19] offset:0
	global_store_dwordx4 v3, v[220:223], s[18:19] offset:16
	v_lshlrev_b32_e32 v224, 16, v196
	v_and_b32_e32 v225, 0xffff0000, v196
	v_lshlrev_b32_e32 v226, 16, v197
	v_and_b32_e32 v227, 0xffff0000, v197
	v_lshlrev_b32_e32 v228, 16, v198
	v_and_b32_e32 v229, 0xffff0000, v198
	v_lshlrev_b32_e32 v230, 16, v199
	v_and_b32_e32 v231, 0xffff0000, v199
	v_pk_mul_f32 v[224:225], v[214:215], v[224:225]
	v_pk_mul_f32 v[226:227], v[214:215], v[226:227]
	v_pk_mul_f32 v[228:229], v[214:215], v[228:229]
	v_pk_mul_f32 v[230:231], v[214:215], v[230:231]
	v_pk_mul_f32 v[224:225], v[64:65], v[224:225]
	v_pk_mul_f32 v[226:227], v[66:67], v[226:227]
	v_pk_mul_f32 v[228:229], v[68:69], v[228:229]
	v_pk_mul_f32 v[230:231], v[70:71], v[230:231]
	global_store_dwordx4 v3, v[224:227], s[18:19] offset:2048
	global_store_dwordx4 v3, v[228:231], s[18:19] offset:2064
	s_endpgm
